# attention QK phase: one counted lgkmcnt wait per MFMA pair (12 fewer s_waitcnt per iteration)
# baseline (speedup 1.0000x reference)
; __device__ __forceinline__ void attn_unit(LAS char* lds, const bf16_t* Qp, const bf16_t* KVp, const bf16_t* KRp, int ntiles, bf16_t* Yp, bool dry) {
;     ...
;         AT_QK(sb0, pa0, pa1);
;         AT_QK(sb0 + 1, pb0, pb1);
.Latt_noload:
	ds_read_b128 v[66:69], v0 offset:0
	ds_read_b128 v[70:73], v0 offset:6656
	ds_read_b128 v[74:77], v0 offset:32
	ds_read_b128 v[78:81], v0 offset:6688
	ds_read_b128 v[212:215], v0 offset:64
	ds_read_b128 v[240:243], v0 offset:6720
	ds_read_b128 v[244:247], v0 offset:96
	s_waitcnt lgkmcnt(5)
	v_mfma_f32_32x32x16_bf16 v[114:129], v[66:69], v[154:157], v[82:97]
	ds_read_b128 v[248:251], v0 offset:6752
	v_mfma_f32_32x32x16_bf16 v[98:113], v[70:73], v[154:157], v[82:97]
	ds_read_b128 v[66:69], v0 offset:128
	s_waitcnt lgkmcnt(5)
	v_mfma_f32_32x32x16_bf16 v[114:129], v[74:77], v[158:161], v[114:129]
	ds_read_b128 v[70:73], v0 offset:6784
	v_mfma_f32_32x32x16_bf16 v[98:113], v[78:81], v[158:161], v[98:113]
	ds_read_b128 v[74:77], v0 offset:160
	s_waitcnt lgkmcnt(5)
	v_mfma_f32_32x32x16_bf16 v[114:129], v[212:215], v[162:165], v[114:129]
	ds_read_b128 v[78:81], v0 offset:6816
	v_mfma_f32_32x32x16_bf16 v[98:113], v[240:243], v[162:165], v[98:113]
	ds_read_b128 v[212:215], v0 offset:13312
	s_waitcnt lgkmcnt(5)
	v_mfma_f32_32x32x16_bf16 v[114:129], v[244:247], v[166:169], v[114:129]
	ds_read_b128 v[240:243], v0 offset:19968
	v_mfma_f32_32x32x16_bf16 v[98:113], v[248:251], v[166:169], v[98:113]
	ds_read_b128 v[244:247], v0 offset:13344
	s_waitcnt lgkmcnt(5)
	v_mfma_f32_32x32x16_bf16 v[114:129], v[66:69], v[170:173], v[114:129]
	ds_read_b128 v[248:251], v0 offset:20000
	v_mfma_f32_32x32x16_bf16 v[98:113], v[70:73], v[170:173], v[98:113]
	ds_read_b128 v[66:69], v0 offset:13376
	s_waitcnt lgkmcnt(5)
	v_mfma_f32_32x32x16_bf16 v[114:129], v[74:77], v[174:177], v[114:129]
	ds_read_b128 v[70:73], v0 offset:20032
	v_mfma_f32_32x32x16_bf16 v[98:113], v[78:81], v[174:177], v[98:113]
	ds_read_b128 v[74:77], v0 offset:13408
	s_waitcnt lgkmcnt(5)
	v_mfma_f32_32x32x16_bf16 v[2:17], v[212:215], v[154:157], v[82:97]
	ds_read_b128 v[78:81], v0 offset:20064
	v_mfma_f32_32x32x16_bf16 v[18:33], v[240:243], v[154:157], v[82:97]
	ds_read_b128 v[212:215], v0 offset:13440
	s_waitcnt lgkmcnt(5)
	v_mfma_f32_32x32x16_bf16 v[2:17], v[244:247], v[158:161], v[2:17]
	ds_read_b128 v[240:243], v0 offset:20096
	v_mfma_f32_32x32x16_bf16 v[18:33], v[248:251], v[158:161], v[18:33]
	ds_read_b128 v[244:247], v0 offset:13472
	s_waitcnt lgkmcnt(5)
	v_mfma_f32_32x32x16_bf16 v[2:17], v[66:69], v[162:165], v[2:17]
	ds_read_b128 v[248:251], v0 offset:20128
	v_mfma_f32_32x32x16_bf16 v[18:33], v[70:73], v[162:165], v[18:33]
	ds_read_b64_tr_b16 v[216:217], v185 offset:53248
	ds_read_b64_tr_b16 v[218:219], v185 offset:53760
	s_waitcnt lgkmcnt(6)
	v_mfma_f32_32x32x16_bf16 v[2:17], v[74:77], v[166:169], v[2:17]
	ds_read_b64_tr_b16 v[220:221], v185 offset:57344
	ds_read_b64_tr_b16 v[222:223], v185 offset:57856
	v_mfma_f32_32x32x16_bf16 v[18:33], v[78:81], v[166:169], v[18:33]
	ds_read_b64_tr_b16 v[224:225], v185 offset:54272
	ds_read_b64_tr_b16 v[226:227], v185 offset:54784
	s_waitcnt lgkmcnt(8)
	v_mfma_f32_32x32x16_bf16 v[2:17], v[212:215], v[170:173], v[2:17]
	ds_read_b64_tr_b16 v[228:229], v185 offset:58368
	ds_read_b64_tr_b16 v[230:231], v185 offset:58880
	v_mfma_f32_32x32x16_bf16 v[18:33], v[240:243], v[170:173], v[18:33]
	ds_read_b64_tr_b16 v[232:233], v185 offset:55296
	ds_read_b64_tr_b16 v[234:235], v185 offset:55808
	s_waitcnt lgkmcnt(10)
	v_mfma_f32_32x32x16_bf16 v[2:17], v[244:247], v[174:177], v[2:17]
	ds_read_b64_tr_b16 v[236:237], v185 offset:59392
	ds_read_b64_tr_b16 v[238:239], v185 offset:59904
	v_mfma_f32_32x32x16_bf16 v[18:33], v[248:251], v[174:177], v[18:33]
	s_cmp_lg_u32 s35, 34
	s_cbranch_scc1 .Latt_nogate
	s_mul_i32 s14, s28, 0x1c00
	s_mul_hi_u32 s15, s25, 0x1c00
	s_add_i32 s15, s15, s14
	s_mul_i32 s14, s25, 0x1c00
	s_add_u32 s14, s88, s14
	s_addc_u32 s15, s89, s15
	s_lshl_b32 s2, s34, 1
	s_add_u32 s14, s14, s2
	s_addc_u32 s15, s15, 0
	v_lshlrev_b32_e32 v146, 1, v196
	v_mov_b32_e32 v147, 0
	s_mov_b64 s[2:3], 0x1000
	v_lshl_add_u64 v[146:147], s[14:15], 0, v[146:147]
	v_lshrrev_b32_e32 v148, 3, v191
	v_lshl_add_u64 v[146:147], v[146:147], 0, s[2:3]
	v_or_b32_e32 v148, s24, v148
	v_mad_i64_i32 v[150:151], s[16:17], v148, s13, v[146:147]
	v_or_b32_e32 v149, 8, v148
	global_load_dwordx4 v[130:133], v[150:151], off
	v_mad_i64_i32 v[152:153], s[16:17], v149, s13, v[146:147]
	v_or_b32_e32 v149, 16, v148
	global_load_dwordx4 v[134:137], v[152:153], off
	v_mad_i64_i32 v[150:151], s[16:17], v149, s13, v[146:147]
	v_or_b32_e32 v149, 24, v148
	global_load_dwordx4 v[138:141], v[150:151], off
	v_mad_i64_i32 v[152:153], s[16:17], v149, s13, v[146:147]
	s_nop 0
	global_load_dwordx4 v[142:145], v[152:153], off
